# hot loop heads (three GEMM K loops, MLA and FOX interior loops) aligned to 64 bytes with s_nop fill
# baseline (speedup 1.0000x reference)
.LBB0_265:
	v_pk_add_f32 v[50:51], v[50:51], v[144:145]
	v_pk_add_f32 v[52:53], v[52:53], v[36:37]
	v_pk_add_f32 v[54:55], v[54:55], v[38:39]
	v_pk_add_f32 v[56:57], v[56:57], v[40:41]
	v_pk_add_f32 v[58:59], v[58:59], v[42:43]
	v_pk_add_f32 v[60:61], v[60:61], v[44:45]
	v_pk_add_f32 v[62:63], v[62:63], v[46:47]
	v_add_f32_e32 v32, v48, v112
	v_add_f32_e32 v33, v49, v125
	v_pk_add_f32 v[50:51], v[50:51], v[52:53]
	v_pk_add_f32 v[54:55], v[54:55], v[56:57]
	v_pk_add_f32 v[58:59], v[58:59], v[60:61]
	v_add_f32_e32 v32, v32, v33
	v_pk_add_f32 v[50:51], v[50:51], v[54:55]
	v_pk_add_f32 v[58:59], v[58:59], v[62:63]
	v_pk_add_f32 v[50:51], v[50:51], v[58:59]
	v_add_f32_e32 v32, v32, v50
	v_add_f32_e32 v32, v32, v51
	s_add_i32 s18, s18, 1
	v_add_f32_e32 v136, v136, v32
	v_add_u32_e32 v143, 64, v143
	s_cmp_ge_i32 s18, s3
	v_add_u32_e32 v124, 64, v124
	s_waitcnt vmcnt(0)
	s_waitcnt lgkmcnt(0)
	s_barrier
	s_cbranch_scc1 .LBB0_274
	.p2alignl 6, 3212836864

.LBB0_349:
	v_pk_add_f32 v[66:67], v[66:67], v[200:201]
	v_pk_add_f32 v[68:69], v[68:69], v[6:7]
	v_pk_add_f32 v[70:71], v[70:71], v[8:9]
	v_pk_add_f32 v[72:73], v[72:73], v[10:11]
	v_pk_add_f32 v[74:75], v[74:75], v[12:13]
	v_pk_add_f32 v[76:77], v[76:77], v[14:15]
	v_pk_add_f32 v[78:79], v[78:79], v[16:17]
	v_add_f32_e32 v3, v64, v115
	v_add_f32_e32 v4, v65, v171
	v_pk_add_f32 v[66:67], v[66:67], v[68:69]
	v_pk_add_f32 v[70:71], v[70:71], v[72:73]
	v_pk_add_f32 v[74:75], v[74:75], v[76:77]
	v_add_f32_e32 v3, v3, v4
	v_pk_add_f32 v[66:67], v[66:67], v[70:71]
	v_pk_add_f32 v[74:75], v[74:75], v[78:79]
	v_pk_add_f32 v[66:67], v[66:67], v[74:75]
	v_add_f32_e32 v3, v3, v66
	v_add_f32_e32 v3, v3, v67
	s_add_i32 s2, s2, 1
	v_add_f32_e32 v163, v163, v3
	v_add_u32_e32 v114, 64, v114
	s_cmp_eq_u32 s22, s2
	v_add_u32_e32 v170, 64, v170
	s_waitcnt vmcnt(0)
	s_waitcnt lgkmcnt(0)
	s_barrier
	s_cbranch_scc1 .LBB0_358
	.p2alignl 6, 3212836864

.Lzp2_go:
	s_add_u32 s18, s18, 0x80
	s_addc_u32 s19, s19, 0
	s_add_u32 s35, s20, 0x100
	s_addc_u32 s38, s21, 0
	s_mov_b32 s20, 0
	s_add_i32 s39, s20, 2
	s_add_u32 s40, s18, 0x80
	s_addc_u32 s21, s19, 0
	s_add_i32 s51, s33, 0x100
	s_cmp_eq_u32 s47, s20
	s_cselect_b32 s21, s1, s21
	s_cselect_b32 s20, s0, s40
	v_add_u32_e32 v152, s51, v155
	s_cselect_b32 s41, s17, s38
	s_cselect_b32 s40, s16, s35
	s_add_i32 s52, s29, 0x100
	ds_read_b128 v[130:133], v152
	ds_read_b128 v[144:147], v152 offset:1024
	ds_read_b128 v[148:151], v152 offset:2048
	ds_read_b128 v[192:195], v152 offset:3072
	v_add_u32_e32 v152, s52, v155
	ds_read_b128 v[196:199], v152
	ds_read_b128 v[200:203], v152 offset:1024
	ds_read_b128 v[204:207], v152 offset:2048
	ds_read_b128 v[208:211], v152 offset:3072
	v_lshl_add_u64 v[152:153], s[18:19], 0, v[140:141]
	s_add_i32 m0, s27, 0xc000
	ds_read_b128 v[212:215], v165
	ds_read_b128 v[216:219], v165 offset:1024
	ds_read_b128 v[220:223], v165 offset:2048
	ds_read_b128 v[224:227], v165 offset:3072
	ds_read_b128 v[228:231], v165 offset:4096
	ds_read_b128 v[232:235], v165 offset:5120
	ds_read_b128 v[236:239], v165 offset:6144
	ds_read_b128 v[240:243], v165 offset:7168
	global_load_lds_dwordx4 v[152:153], off
	v_lshl_add_u64 v[152:153], s[18:19], 0, v[142:143]
	s_add_i32 m0, s27, 0xe000
	s_nop 0
	global_load_lds_dwordx4 v[152:153], off
	s_waitcnt vmcnt(8)
	s_waitcnt lgkmcnt(0)
	s_barrier
	s_setprio 1
	s_waitcnt lgkmcnt(0)
	v_mfma_f32_16x16x32_bf16 v[126:129], v[130:133], v[212:215], 0
	v_mfma_f32_16x16x32_bf16 v[122:125], v[148:151], v[212:215], 0
	v_mfma_f32_16x16x32_bf16 v[108:111], v[130:133], v[220:223], 0
	v_mfma_f32_16x16x32_bf16 v[104:107], v[148:151], v[220:223], 0
	v_mfma_f32_16x16x32_bf16 v[92:95], v[130:133], v[228:231], 0
	v_mfma_f32_16x16x32_bf16 v[88:91], v[148:151], v[228:231], 0
	v_mfma_f32_16x16x32_bf16 v[76:79], v[130:133], v[236:239], 0
	v_mfma_f32_16x16x32_bf16 v[72:75], v[148:151], v[236:239], 0
	v_mfma_f32_16x16x32_bf16 v[126:129], v[144:147], v[216:219], v[126:129]
	v_mfma_f32_16x16x32_bf16 v[122:125], v[192:195], v[216:219], v[122:125]
	v_mfma_f32_16x16x32_bf16 v[108:111], v[144:147], v[224:227], v[108:111]
	v_mfma_f32_16x16x32_bf16 v[104:107], v[192:195], v[224:227], v[104:107]
	v_mfma_f32_16x16x32_bf16 v[92:95], v[144:147], v[232:235], v[92:95]
	v_mfma_f32_16x16x32_bf16 v[88:91], v[192:195], v[232:235], v[88:91]
	v_mfma_f32_16x16x32_bf16 v[76:79], v[144:147], v[240:243], v[76:79]
	v_mfma_f32_16x16x32_bf16 v[72:75], v[192:195], v[240:243], v[72:75]
	s_setprio 0
	s_setprio 1
	v_mfma_f32_16x16x32_bf16 v[118:121], v[196:199], v[212:215], 0
	v_mfma_f32_16x16x32_bf16 v[114:117], v[204:207], v[212:215], 0
	v_mfma_f32_16x16x32_bf16 v[100:103], v[196:199], v[220:223], 0
	v_mfma_f32_16x16x32_bf16 v[96:99], v[204:207], v[220:223], 0
	v_mfma_f32_16x16x32_bf16 v[84:87], v[196:199], v[228:231], 0
	v_mfma_f32_16x16x32_bf16 v[80:83], v[204:207], v[228:231], 0
	v_mfma_f32_16x16x32_bf16 v[68:71], v[196:199], v[236:239], 0
	v_mfma_f32_16x16x32_bf16 v[64:67], v[204:207], v[236:239], 0
	v_mfma_f32_16x16x32_bf16 v[118:121], v[200:203], v[216:219], v[118:121]
	v_mfma_f32_16x16x32_bf16 v[114:117], v[208:211], v[216:219], v[114:117]
	v_mfma_f32_16x16x32_bf16 v[100:103], v[200:203], v[224:227], v[100:103]
	v_mfma_f32_16x16x32_bf16 v[96:99], v[208:211], v[224:227], v[96:99]
	v_mfma_f32_16x16x32_bf16 v[84:87], v[200:203], v[232:235], v[84:87]
	v_mfma_f32_16x16x32_bf16 v[80:83], v[208:211], v[232:235], v[80:83]
	v_mfma_f32_16x16x32_bf16 v[68:71], v[200:203], v[240:243], v[68:71]
	v_mfma_f32_16x16x32_bf16 v[64:67], v[208:211], v[240:243], v[64:67]
	s_setprio 0
	s_barrier
	s_add_i32 s51, s51, s26
	v_lshl_add_u64 v[152:153], s[40:41], 0, v[112:113]
	s_mov_b32 m0, s51
	ds_read_b128 v[212:215], v165 offset:16384
	ds_read_b128 v[216:219], v165 offset:17408
	ds_read_b128 v[220:223], v165 offset:18432
	ds_read_b128 v[224:227], v165 offset:19456
	ds_read_b128 v[228:231], v165 offset:20480
	ds_read_b128 v[232:235], v165 offset:21504
	ds_read_b128 v[236:239], v165 offset:22528
	ds_read_b128 v[240:243], v165 offset:23552
	global_load_lds_dwordx4 v[152:153], off
	s_add_i32 m0, s51, 0x2000
	v_lshl_add_u64 v[170:171], s[40:41], 0, v[134:135]
	s_add_u32 s40, s40, s2
	s_addc_u32 s41, s41, 0
	s_add_i32 s51, s52, s26
	global_load_lds_dwordx4 v[170:171], off
	v_lshl_add_u64 v[176:177], s[40:41], 0, v[112:113]
	s_mov_b32 m0, s51
	v_lshl_add_u64 v[178:179], s[40:41], 0, v[134:135]
	global_load_lds_dwordx4 v[176:177], off
	s_add_i32 m0, s51, 0x2000
	v_lshl_add_u64 v[180:181], s[20:21], 0, v[138:139]
	global_load_lds_dwordx4 v[178:179], off
	s_mov_b32 m0, s27
	v_lshl_add_u64 v[244:245], s[20:21], 0, v[136:137]
	global_load_lds_dwordx4 v[180:181], off
	s_mov_b32 m0, s42
	s_nop 0
	global_load_lds_dwordx4 v[244:245], off
	s_waitcnt vmcnt(8)
	s_waitcnt lgkmcnt(0)
	s_barrier
	s_setprio 1
	s_waitcnt lgkmcnt(0)
	v_mfma_f32_16x16x32_bf16 v[60:63], v[130:133], v[212:215], 0
	v_mfma_f32_16x16x32_bf16 v[56:59], v[148:151], v[212:215], 0
	v_mfma_f32_16x16x32_bf16 v[44:47], v[130:133], v[220:223], 0
	v_mfma_f32_16x16x32_bf16 v[40:43], v[148:151], v[220:223], 0
	v_mfma_f32_16x16x32_bf16 v[28:31], v[130:133], v[228:231], 0
	v_mfma_f32_16x16x32_bf16 v[24:27], v[148:151], v[228:231], 0
	v_mfma_f32_16x16x32_bf16 v[12:15], v[130:133], v[236:239], 0
	v_mfma_f32_16x16x32_bf16 v[8:11], v[148:151], v[236:239], 0
	v_mfma_f32_16x16x32_bf16 v[60:63], v[144:147], v[216:219], v[60:63]
	v_mfma_f32_16x16x32_bf16 v[56:59], v[192:195], v[216:219], v[56:59]
	v_mfma_f32_16x16x32_bf16 v[44:47], v[144:147], v[224:227], v[44:47]
	v_mfma_f32_16x16x32_bf16 v[40:43], v[192:195], v[224:227], v[40:43]
	v_mfma_f32_16x16x32_bf16 v[28:31], v[144:147], v[232:235], v[28:31]
	v_mfma_f32_16x16x32_bf16 v[24:27], v[192:195], v[232:235], v[24:27]
	v_mfma_f32_16x16x32_bf16 v[12:15], v[144:147], v[240:243], v[12:15]
	v_mfma_f32_16x16x32_bf16 v[8:11], v[192:195], v[240:243], v[8:11]
	s_setprio 0
	s_setprio 1
	v_mfma_f32_16x16x32_bf16 v[52:55], v[196:199], v[212:215], 0
	v_mfma_f32_16x16x32_bf16 v[48:51], v[204:207], v[212:215], 0
	v_mfma_f32_16x16x32_bf16 v[36:39], v[196:199], v[220:223], 0
	v_mfma_f32_16x16x32_bf16 v[32:35], v[204:207], v[220:223], 0
	v_mfma_f32_16x16x32_bf16 v[20:23], v[196:199], v[228:231], 0
	v_mfma_f32_16x16x32_bf16 v[16:19], v[204:207], v[228:231], 0
	v_mfma_f32_16x16x32_bf16 v[4:7], v[196:199], v[236:239], 0
	v_mfma_f32_16x16x32_bf16 v[0:3], v[204:207], v[236:239], 0
	v_mfma_f32_16x16x32_bf16 v[52:55], v[200:203], v[216:219], v[52:55]
	v_mfma_f32_16x16x32_bf16 v[48:51], v[208:211], v[216:219], v[48:51]
	v_mfma_f32_16x16x32_bf16 v[36:39], v[200:203], v[224:227], v[36:39]
	v_mfma_f32_16x16x32_bf16 v[32:35], v[208:211], v[224:227], v[32:35]
	v_mfma_f32_16x16x32_bf16 v[20:23], v[200:203], v[232:235], v[20:23]
	v_mfma_f32_16x16x32_bf16 v[16:19], v[208:211], v[232:235], v[16:19]
	v_mfma_f32_16x16x32_bf16 v[4:7], v[200:203], v[240:243], v[4:7]
	v_mfma_f32_16x16x32_bf16 v[0:3], v[208:211], v[240:243], v[0:3]
	s_setprio 0
	s_barrier
	s_add_i32 s40, s8, 0x100
	v_add_u32_e32 v191, s40, v155
	s_add_i32 s41, s9, 0x100
	ds_read_b128 v[130:133], v191
	ds_read_b128 v[144:147], v191 offset:1024
	ds_read_b128 v[148:151], v191 offset:2048
	ds_read_b128 v[192:195], v191 offset:3072
	v_add_u32_e32 v191, s41, v155
	ds_read_b128 v[196:199], v191
	ds_read_b128 v[200:203], v191 offset:1024
	ds_read_b128 v[204:207], v191 offset:2048
	ds_read_b128 v[208:211], v191 offset:3072
	s_add_u32 s20, s20, s2
	s_addc_u32 s21, s21, 0
	s_mov_b32 m0, s43
	v_lshl_add_u64 v[246:247], s[20:21], 0, v[138:139]
	ds_read_b128 v[212:215], v165 offset:32768
	ds_read_b128 v[216:219], v165 offset:33792
	ds_read_b128 v[220:223], v165 offset:34816
	ds_read_b128 v[224:227], v165 offset:35840
	ds_read_b128 v[228:231], v165 offset:36864
	ds_read_b128 v[232:235], v165 offset:37888
	ds_read_b128 v[236:239], v165 offset:38912
	ds_read_b128 v[240:243], v165 offset:39936
	global_load_lds_dwordx4 v[246:247], off
	v_lshl_add_u64 v[246:247], s[20:21], 0, v[136:137]
	s_mov_b32 m0, s44
	s_nop 0
	global_load_lds_dwordx4 v[246:247], off
	s_waitcnt vmcnt(8)
	s_waitcnt lgkmcnt(0)
	s_barrier
	s_setprio 1
	s_waitcnt lgkmcnt(0)
	v_mfma_f32_16x16x32_bf16 v[126:129], v[130:133], v[212:215], v[126:129]
	v_mfma_f32_16x16x32_bf16 v[122:125], v[148:151], v[212:215], v[122:125]
	v_mfma_f32_16x16x32_bf16 v[108:111], v[130:133], v[220:223], v[108:111]
	v_mfma_f32_16x16x32_bf16 v[104:107], v[148:151], v[220:223], v[104:107]
	v_mfma_f32_16x16x32_bf16 v[92:95], v[130:133], v[228:231], v[92:95]
	v_mfma_f32_16x16x32_bf16 v[88:91], v[148:151], v[228:231], v[88:91]
	v_mfma_f32_16x16x32_bf16 v[76:79], v[130:133], v[236:239], v[76:79]
	v_mfma_f32_16x16x32_bf16 v[72:75], v[148:151], v[236:239], v[72:75]
	v_mfma_f32_16x16x32_bf16 v[126:129], v[144:147], v[216:219], v[126:129]
	v_mfma_f32_16x16x32_bf16 v[122:125], v[192:195], v[216:219], v[122:125]
	v_mfma_f32_16x16x32_bf16 v[108:111], v[144:147], v[224:227], v[108:111]
	v_mfma_f32_16x16x32_bf16 v[104:107], v[192:195], v[224:227], v[104:107]
	v_mfma_f32_16x16x32_bf16 v[92:95], v[144:147], v[232:235], v[92:95]
	v_mfma_f32_16x16x32_bf16 v[88:91], v[192:195], v[232:235], v[88:91]
	v_mfma_f32_16x16x32_bf16 v[76:79], v[144:147], v[240:243], v[76:79]
	v_mfma_f32_16x16x32_bf16 v[72:75], v[192:195], v[240:243], v[72:75]
	s_setprio 0
	s_setprio 1
	v_mfma_f32_16x16x32_bf16 v[118:121], v[196:199], v[212:215], v[118:121]
	v_mfma_f32_16x16x32_bf16 v[114:117], v[204:207], v[212:215], v[114:117]
	v_mfma_f32_16x16x32_bf16 v[100:103], v[196:199], v[220:223], v[100:103]
	v_mfma_f32_16x16x32_bf16 v[96:99], v[204:207], v[220:223], v[96:99]
	v_mfma_f32_16x16x32_bf16 v[84:87], v[196:199], v[228:231], v[84:87]
	v_mfma_f32_16x16x32_bf16 v[80:83], v[204:207], v[228:231], v[80:83]
	v_mfma_f32_16x16x32_bf16 v[68:71], v[196:199], v[236:239], v[68:71]
	v_mfma_f32_16x16x32_bf16 v[64:67], v[204:207], v[236:239], v[64:67]
	v_mfma_f32_16x16x32_bf16 v[118:121], v[200:203], v[216:219], v[118:121]
	v_mfma_f32_16x16x32_bf16 v[114:117], v[208:211], v[216:219], v[114:117]
	v_mfma_f32_16x16x32_bf16 v[100:103], v[200:203], v[224:227], v[100:103]
	v_mfma_f32_16x16x32_bf16 v[96:99], v[208:211], v[224:227], v[96:99]
	v_mfma_f32_16x16x32_bf16 v[84:87], v[200:203], v[232:235], v[84:87]
	v_mfma_f32_16x16x32_bf16 v[80:83], v[208:211], v[232:235], v[80:83]
	v_mfma_f32_16x16x32_bf16 v[68:71], v[200:203], v[240:243], v[68:71]
	v_mfma_f32_16x16x32_bf16 v[64:67], v[208:211], v[240:243], v[64:67]
	s_setprio 0
	s_barrier
	s_add_i32 s20, s40, s26
	v_lshl_add_u64 v[152:153], v[152:153], 0, s[30:31]
	s_mov_b32 m0, s20
	ds_read_b128 v[212:215], v165 offset:49152
	ds_read_b128 v[216:219], v165 offset:50176
	ds_read_b128 v[220:223], v165 offset:51200
	ds_read_b128 v[224:227], v165 offset:52224
	ds_read_b128 v[228:231], v165 offset:53248
	ds_read_b128 v[232:235], v165 offset:54272
	ds_read_b128 v[236:239], v165 offset:55296
	ds_read_b128 v[240:243], v165 offset:56320
	global_load_lds_dwordx4 v[152:153], off
	v_lshl_add_u64 v[152:153], v[170:171], 0, s[30:31]
	s_add_i32 m0, s20, 0x2000
	s_add_i32 s20, s41, s26
	global_load_lds_dwordx4 v[152:153], off
	v_lshl_add_u64 v[152:153], v[176:177], 0, s[30:31]
	s_mov_b32 m0, s20
	s_nop 0
	global_load_lds_dwordx4 v[152:153], off
	v_lshl_add_u64 v[152:153], v[178:179], 0, s[30:31]
	s_add_i32 m0, s20, 0x2000
	s_nop 0
	global_load_lds_dwordx4 v[152:153], off
	v_lshl_add_u64 v[152:153], v[180:181], 0, s[30:31]
	s_mov_b32 m0, s45
	s_nop 0
	global_load_lds_dwordx4 v[152:153], off
	v_lshl_add_u64 v[152:153], v[244:245], 0, s[30:31]
	s_mov_b32 m0, s46
	s_nop 0
	global_load_lds_dwordx4 v[152:153], off
	s_waitcnt vmcnt(8)
	s_waitcnt lgkmcnt(0)
	s_barrier
	s_setprio 1
	s_waitcnt lgkmcnt(0)
	v_mfma_f32_16x16x32_bf16 v[60:63], v[130:133], v[212:215], v[60:63]
	v_mfma_f32_16x16x32_bf16 v[56:59], v[148:151], v[212:215], v[56:59]
	v_mfma_f32_16x16x32_bf16 v[44:47], v[130:133], v[220:223], v[44:47]
	v_mfma_f32_16x16x32_bf16 v[40:43], v[148:151], v[220:223], v[40:43]
	v_mfma_f32_16x16x32_bf16 v[28:31], v[130:133], v[228:231], v[28:31]
	v_mfma_f32_16x16x32_bf16 v[24:27], v[148:151], v[228:231], v[24:27]
	v_mfma_f32_16x16x32_bf16 v[12:15], v[130:133], v[236:239], v[12:15]
	v_mfma_f32_16x16x32_bf16 v[8:11], v[148:151], v[236:239], v[8:11]
	v_mfma_f32_16x16x32_bf16 v[60:63], v[144:147], v[216:219], v[60:63]
	v_mfma_f32_16x16x32_bf16 v[56:59], v[192:195], v[216:219], v[56:59]
	v_mfma_f32_16x16x32_bf16 v[44:47], v[144:147], v[224:227], v[44:47]
	v_mfma_f32_16x16x32_bf16 v[40:43], v[192:195], v[224:227], v[40:43]
	v_mfma_f32_16x16x32_bf16 v[28:31], v[144:147], v[232:235], v[28:31]
	v_mfma_f32_16x16x32_bf16 v[24:27], v[192:195], v[232:235], v[24:27]
	v_mfma_f32_16x16x32_bf16 v[12:15], v[144:147], v[240:243], v[12:15]
	v_mfma_f32_16x16x32_bf16 v[8:11], v[192:195], v[240:243], v[8:11]
	s_setprio 0
	s_setprio 1
	v_mfma_f32_16x16x32_bf16 v[52:55], v[196:199], v[212:215], v[52:55]
	v_mfma_f32_16x16x32_bf16 v[48:51], v[204:207], v[212:215], v[48:51]
	v_mfma_f32_16x16x32_bf16 v[36:39], v[196:199], v[220:223], v[36:39]
	v_mfma_f32_16x16x32_bf16 v[32:35], v[204:207], v[220:223], v[32:35]
	v_mfma_f32_16x16x32_bf16 v[20:23], v[196:199], v[228:231], v[20:23]
	v_mfma_f32_16x16x32_bf16 v[16:19], v[204:207], v[228:231], v[16:19]
	v_mfma_f32_16x16x32_bf16 v[4:7], v[196:199], v[236:239], v[4:7]
	v_mfma_f32_16x16x32_bf16 v[0:3], v[204:207], v[236:239], v[0:3]
	v_mfma_f32_16x16x32_bf16 v[52:55], v[200:203], v[216:219], v[52:55]
	v_mfma_f32_16x16x32_bf16 v[48:51], v[208:211], v[216:219], v[48:51]
	v_mfma_f32_16x16x32_bf16 v[36:39], v[200:203], v[224:227], v[36:39]
	v_mfma_f32_16x16x32_bf16 v[32:35], v[208:211], v[224:227], v[32:35]
	v_mfma_f32_16x16x32_bf16 v[20:23], v[200:203], v[232:235], v[20:23]
	v_mfma_f32_16x16x32_bf16 v[16:19], v[208:211], v[232:235], v[16:19]
	v_mfma_f32_16x16x32_bf16 v[4:7], v[200:203], v[240:243], v[4:7]
	v_mfma_f32_16x16x32_bf16 v[0:3], v[208:211], v[240:243], v[0:3]
	s_setprio 0
	s_barrier
	s_add_u32 s18, s18, 0x100
	s_addc_u32 s19, s19, 0
	s_add_u32 s35, s35, 0x100
	s_addc_u32 s38, s38, 0
	s_cmp_ge_u32 s39, s34
	s_mov_b32 s20, s39
	s_cbranch_scc1 .Lzp2_done
	.p2alignl 6, 3212836864

.Lzp3_go:
	s_add_u32 s18, s18, 0x80
	s_addc_u32 s19, s19, 0
	s_add_u32 s35, s20, 0x100
	s_addc_u32 s53, s21, 0
	s_mov_b32 s20, 0
	s_add_i32 s54, s20, 2
	s_add_u32 s55, s18, 0x80
	s_addc_u32 s21, s19, 0
	s_add_i32 s58, s33, 0x100
	s_cmp_eq_u32 s45, s20
	s_cselect_b32 s21, s15, s21
	s_cselect_b32 s20, s14, s55
	v_add_u32_e32 v163, s58, v141
	s_cselect_b32 s57, s17, s53
	s_cselect_b32 s56, s16, s35
	s_add_i32 s55, s29, 0x100
	ds_read_b128 v[144:147], v163
	ds_read_b128 v[148:151], v163 offset:1024
	ds_read_b128 v[152:155], v163 offset:2048
	ds_read_b128 v[192:195], v163 offset:3072
	v_add_u32_e32 v163, s55, v141
	ds_read_b128 v[196:199], v163
	ds_read_b128 v[200:203], v163 offset:1024
	ds_read_b128 v[204:207], v163 offset:2048
	ds_read_b128 v[208:211], v163 offset:3072
	v_lshl_add_u64 v[170:171], s[18:19], 0, v[136:137]
	s_add_i32 m0, s38, 0xc000
	ds_read_b128 v[212:215], v143
	ds_read_b128 v[216:219], v143 offset:1024
	ds_read_b128 v[220:223], v143 offset:2048
	ds_read_b128 v[224:227], v143 offset:3072
	ds_read_b128 v[228:231], v143 offset:4096
	ds_read_b128 v[232:235], v143 offset:5120
	ds_read_b128 v[236:239], v143 offset:6144
	ds_read_b128 v[240:243], v143 offset:7168
	global_load_lds_dwordx4 v[170:171], off
	v_lshl_add_u64 v[170:171], s[18:19], 0, v[138:139]
	s_add_i32 m0, s38, 0xe000
	s_nop 0
	global_load_lds_dwordx4 v[170:171], off
	s_waitcnt vmcnt(8)
	s_waitcnt lgkmcnt(0)
	s_barrier
	s_setprio 1
	s_waitcnt lgkmcnt(0)
	v_mfma_f32_16x16x32_bf16 v[126:129], v[144:147], v[212:215], 0
	v_mfma_f32_16x16x32_bf16 v[122:125], v[152:155], v[212:215], 0
	v_mfma_f32_16x16x32_bf16 v[108:111], v[144:147], v[220:223], 0
	v_mfma_f32_16x16x32_bf16 v[104:107], v[152:155], v[220:223], 0
	v_mfma_f32_16x16x32_bf16 v[92:95], v[144:147], v[228:231], 0
	v_mfma_f32_16x16x32_bf16 v[88:91], v[152:155], v[228:231], 0
	v_mfma_f32_16x16x32_bf16 v[76:79], v[144:147], v[236:239], 0
	v_mfma_f32_16x16x32_bf16 v[72:75], v[152:155], v[236:239], 0
	v_mfma_f32_16x16x32_bf16 v[126:129], v[148:151], v[216:219], v[126:129]
	v_mfma_f32_16x16x32_bf16 v[122:125], v[192:195], v[216:219], v[122:125]
	v_mfma_f32_16x16x32_bf16 v[108:111], v[148:151], v[224:227], v[108:111]
	v_mfma_f32_16x16x32_bf16 v[104:107], v[192:195], v[224:227], v[104:107]
	v_mfma_f32_16x16x32_bf16 v[92:95], v[148:151], v[232:235], v[92:95]
	v_mfma_f32_16x16x32_bf16 v[88:91], v[192:195], v[232:235], v[88:91]
	v_mfma_f32_16x16x32_bf16 v[76:79], v[148:151], v[240:243], v[76:79]
	v_mfma_f32_16x16x32_bf16 v[72:75], v[192:195], v[240:243], v[72:75]
	s_setprio 0
	s_setprio 1
	v_mfma_f32_16x16x32_bf16 v[118:121], v[196:199], v[212:215], 0
	v_mfma_f32_16x16x32_bf16 v[114:117], v[204:207], v[212:215], 0
	v_mfma_f32_16x16x32_bf16 v[100:103], v[196:199], v[220:223], 0
	v_mfma_f32_16x16x32_bf16 v[96:99], v[204:207], v[220:223], 0
	v_mfma_f32_16x16x32_bf16 v[84:87], v[196:199], v[228:231], 0
	v_mfma_f32_16x16x32_bf16 v[80:83], v[204:207], v[228:231], 0
	v_mfma_f32_16x16x32_bf16 v[68:71], v[196:199], v[236:239], 0
	v_mfma_f32_16x16x32_bf16 v[64:67], v[204:207], v[236:239], 0
	v_mfma_f32_16x16x32_bf16 v[118:121], v[200:203], v[216:219], v[118:121]
	v_mfma_f32_16x16x32_bf16 v[114:117], v[208:211], v[216:219], v[114:117]
	v_mfma_f32_16x16x32_bf16 v[100:103], v[200:203], v[224:227], v[100:103]
	v_mfma_f32_16x16x32_bf16 v[96:99], v[208:211], v[224:227], v[96:99]
	v_mfma_f32_16x16x32_bf16 v[84:87], v[200:203], v[232:235], v[84:87]
	v_mfma_f32_16x16x32_bf16 v[80:83], v[208:211], v[232:235], v[80:83]
	v_mfma_f32_16x16x32_bf16 v[68:71], v[200:203], v[240:243], v[68:71]
	v_mfma_f32_16x16x32_bf16 v[64:67], v[208:211], v[240:243], v[64:67]
	s_setprio 0
	s_barrier
	s_add_i32 s58, s58, s27
	v_lshl_add_u64 v[170:171], s[56:57], 0, v[112:113]
	s_mov_b32 m0, s58
	ds_read_b128 v[212:215], v143 offset:16384
	ds_read_b128 v[216:219], v143 offset:17408
	ds_read_b128 v[220:223], v143 offset:18432
	ds_read_b128 v[224:227], v143 offset:19456
	ds_read_b128 v[228:231], v143 offset:20480
	ds_read_b128 v[232:235], v143 offset:21504
	ds_read_b128 v[236:239], v143 offset:22528
	ds_read_b128 v[240:243], v143 offset:23552
	global_load_lds_dwordx4 v[170:171], off
	s_add_i32 m0, s58, 0x2000
	v_lshl_add_u64 v[176:177], s[56:57], 0, v[130:131]
	s_add_u32 s56, s56, s2
	s_addc_u32 s57, s57, 0
	s_add_i32 s55, s55, s27
	global_load_lds_dwordx4 v[176:177], off
	v_lshl_add_u64 v[178:179], s[56:57], 0, v[112:113]
	s_mov_b32 m0, s55
	v_lshl_add_u64 v[180:181], s[56:57], 0, v[130:131]
	global_load_lds_dwordx4 v[178:179], off
	s_add_i32 m0, s55, 0x2000
	v_lshl_add_u64 v[244:245], s[20:21], 0, v[134:135]
	global_load_lds_dwordx4 v[180:181], off
	s_mov_b32 m0, s38
	v_lshl_add_u64 v[246:247], s[20:21], 0, v[132:133]
	global_load_lds_dwordx4 v[244:245], off
	s_mov_b32 m0, s39
	s_nop 0
	global_load_lds_dwordx4 v[246:247], off
	s_waitcnt vmcnt(8)
	s_waitcnt lgkmcnt(0)
	s_barrier
	s_setprio 1
	s_waitcnt lgkmcnt(0)
	v_mfma_f32_16x16x32_bf16 v[60:63], v[144:147], v[212:215], 0
	v_mfma_f32_16x16x32_bf16 v[56:59], v[152:155], v[212:215], 0
	v_mfma_f32_16x16x32_bf16 v[44:47], v[144:147], v[220:223], 0
	v_mfma_f32_16x16x32_bf16 v[40:43], v[152:155], v[220:223], 0
	v_mfma_f32_16x16x32_bf16 v[28:31], v[144:147], v[228:231], 0
	v_mfma_f32_16x16x32_bf16 v[24:27], v[152:155], v[228:231], 0
	v_mfma_f32_16x16x32_bf16 v[12:15], v[144:147], v[236:239], 0
	v_mfma_f32_16x16x32_bf16 v[8:11], v[152:155], v[236:239], 0
	v_mfma_f32_16x16x32_bf16 v[60:63], v[148:151], v[216:219], v[60:63]
	v_mfma_f32_16x16x32_bf16 v[56:59], v[192:195], v[216:219], v[56:59]
	v_mfma_f32_16x16x32_bf16 v[44:47], v[148:151], v[224:227], v[44:47]
	v_mfma_f32_16x16x32_bf16 v[40:43], v[192:195], v[224:227], v[40:43]
	v_mfma_f32_16x16x32_bf16 v[28:31], v[148:151], v[232:235], v[28:31]
	v_mfma_f32_16x16x32_bf16 v[24:27], v[192:195], v[232:235], v[24:27]
	v_mfma_f32_16x16x32_bf16 v[12:15], v[148:151], v[240:243], v[12:15]
	v_mfma_f32_16x16x32_bf16 v[8:11], v[192:195], v[240:243], v[8:11]
	s_setprio 0
	s_setprio 1
	v_mfma_f32_16x16x32_bf16 v[52:55], v[196:199], v[212:215], 0
	v_mfma_f32_16x16x32_bf16 v[48:51], v[204:207], v[212:215], 0
	v_mfma_f32_16x16x32_bf16 v[36:39], v[196:199], v[220:223], 0
	v_mfma_f32_16x16x32_bf16 v[32:35], v[204:207], v[220:223], 0
	v_mfma_f32_16x16x32_bf16 v[20:23], v[196:199], v[228:231], 0
	v_mfma_f32_16x16x32_bf16 v[16:19], v[204:207], v[228:231], 0
	v_mfma_f32_16x16x32_bf16 v[4:7], v[196:199], v[236:239], 0
	v_mfma_f32_16x16x32_bf16 v[0:3], v[204:207], v[236:239], 0
	v_mfma_f32_16x16x32_bf16 v[52:55], v[200:203], v[216:219], v[52:55]
	v_mfma_f32_16x16x32_bf16 v[48:51], v[208:211], v[216:219], v[48:51]
	v_mfma_f32_16x16x32_bf16 v[36:39], v[200:203], v[224:227], v[36:39]
	v_mfma_f32_16x16x32_bf16 v[32:35], v[208:211], v[224:227], v[32:35]
	v_mfma_f32_16x16x32_bf16 v[20:23], v[200:203], v[232:235], v[20:23]
	v_mfma_f32_16x16x32_bf16 v[16:19], v[208:211], v[232:235], v[16:19]
	v_mfma_f32_16x16x32_bf16 v[4:7], v[200:203], v[240:243], v[4:7]
	v_mfma_f32_16x16x32_bf16 v[0:3], v[208:211], v[240:243], v[0:3]
	s_setprio 0
	s_barrier
	s_add_i32 s55, s8, 0x100
	v_add_u32_e32 v163, s55, v141
	s_add_i32 s56, s9, 0x100
	ds_read_b128 v[144:147], v163
	ds_read_b128 v[148:151], v163 offset:1024
	ds_read_b128 v[152:155], v163 offset:2048
	ds_read_b128 v[192:195], v163 offset:3072
	v_add_u32_e32 v163, s56, v141
	ds_read_b128 v[196:199], v163
	ds_read_b128 v[200:203], v163 offset:1024
	ds_read_b128 v[204:207], v163 offset:2048
	ds_read_b128 v[208:211], v163 offset:3072
	s_add_u32 s20, s20, s2
	s_addc_u32 s21, s21, 0
	s_mov_b32 m0, s40
	v_lshl_add_u64 v[248:249], s[20:21], 0, v[134:135]
	ds_read_b128 v[212:215], v143 offset:32768
	ds_read_b128 v[216:219], v143 offset:33792
	ds_read_b128 v[220:223], v143 offset:34816
	ds_read_b128 v[224:227], v143 offset:35840
	ds_read_b128 v[228:231], v143 offset:36864
	ds_read_b128 v[232:235], v143 offset:37888
	ds_read_b128 v[236:239], v143 offset:38912
	ds_read_b128 v[240:243], v143 offset:39936
	global_load_lds_dwordx4 v[248:249], off
	v_lshl_add_u64 v[248:249], s[20:21], 0, v[132:133]
	s_mov_b32 m0, s41
	s_nop 0
	global_load_lds_dwordx4 v[248:249], off
	s_waitcnt vmcnt(8)
	s_waitcnt lgkmcnt(0)
	s_barrier
	s_setprio 1
	s_waitcnt lgkmcnt(0)
	v_mfma_f32_16x16x32_bf16 v[126:129], v[144:147], v[212:215], v[126:129]
	v_mfma_f32_16x16x32_bf16 v[122:125], v[152:155], v[212:215], v[122:125]
	v_mfma_f32_16x16x32_bf16 v[108:111], v[144:147], v[220:223], v[108:111]
	v_mfma_f32_16x16x32_bf16 v[104:107], v[152:155], v[220:223], v[104:107]
	v_mfma_f32_16x16x32_bf16 v[92:95], v[144:147], v[228:231], v[92:95]
	v_mfma_f32_16x16x32_bf16 v[88:91], v[152:155], v[228:231], v[88:91]
	v_mfma_f32_16x16x32_bf16 v[76:79], v[144:147], v[236:239], v[76:79]
	v_mfma_f32_16x16x32_bf16 v[72:75], v[152:155], v[236:239], v[72:75]
	v_mfma_f32_16x16x32_bf16 v[126:129], v[148:151], v[216:219], v[126:129]
	v_mfma_f32_16x16x32_bf16 v[122:125], v[192:195], v[216:219], v[122:125]
	v_mfma_f32_16x16x32_bf16 v[108:111], v[148:151], v[224:227], v[108:111]
	v_mfma_f32_16x16x32_bf16 v[104:107], v[192:195], v[224:227], v[104:107]
	v_mfma_f32_16x16x32_bf16 v[92:95], v[148:151], v[232:235], v[92:95]
	v_mfma_f32_16x16x32_bf16 v[88:91], v[192:195], v[232:235], v[88:91]
	v_mfma_f32_16x16x32_bf16 v[76:79], v[148:151], v[240:243], v[76:79]
	v_mfma_f32_16x16x32_bf16 v[72:75], v[192:195], v[240:243], v[72:75]
	s_setprio 0
	s_setprio 1
	v_mfma_f32_16x16x32_bf16 v[118:121], v[196:199], v[212:215], v[118:121]
	v_mfma_f32_16x16x32_bf16 v[114:117], v[204:207], v[212:215], v[114:117]
	v_mfma_f32_16x16x32_bf16 v[100:103], v[196:199], v[220:223], v[100:103]
	v_mfma_f32_16x16x32_bf16 v[96:99], v[204:207], v[220:223], v[96:99]
	v_mfma_f32_16x16x32_bf16 v[84:87], v[196:199], v[228:231], v[84:87]
	v_mfma_f32_16x16x32_bf16 v[80:83], v[204:207], v[228:231], v[80:83]
	v_mfma_f32_16x16x32_bf16 v[68:71], v[196:199], v[236:239], v[68:71]
	v_mfma_f32_16x16x32_bf16 v[64:67], v[204:207], v[236:239], v[64:67]
	v_mfma_f32_16x16x32_bf16 v[118:121], v[200:203], v[216:219], v[118:121]
	v_mfma_f32_16x16x32_bf16 v[114:117], v[208:211], v[216:219], v[114:117]
	v_mfma_f32_16x16x32_bf16 v[100:103], v[200:203], v[224:227], v[100:103]
	v_mfma_f32_16x16x32_bf16 v[96:99], v[208:211], v[224:227], v[96:99]
	v_mfma_f32_16x16x32_bf16 v[84:87], v[200:203], v[232:235], v[84:87]
	v_mfma_f32_16x16x32_bf16 v[80:83], v[208:211], v[232:235], v[80:83]
	v_mfma_f32_16x16x32_bf16 v[68:71], v[200:203], v[240:243], v[68:71]
	v_mfma_f32_16x16x32_bf16 v[64:67], v[208:211], v[240:243], v[64:67]
	s_setprio 0
	s_barrier
	s_add_i32 s20, s55, s27
	v_lshl_add_u64 v[170:171], v[170:171], 0, s[30:31]
	s_mov_b32 m0, s20
	ds_read_b128 v[212:215], v143 offset:49152
	ds_read_b128 v[216:219], v143 offset:50176
	ds_read_b128 v[220:223], v143 offset:51200
	ds_read_b128 v[224:227], v143 offset:52224
	ds_read_b128 v[228:231], v143 offset:53248
	ds_read_b128 v[232:235], v143 offset:54272
	ds_read_b128 v[236:239], v143 offset:55296
	ds_read_b128 v[240:243], v143 offset:56320
	global_load_lds_dwordx4 v[170:171], off
	v_lshl_add_u64 v[170:171], v[176:177], 0, s[30:31]
	s_add_i32 m0, s20, 0x2000
	s_add_i32 s20, s56, s27
	global_load_lds_dwordx4 v[170:171], off
	v_lshl_add_u64 v[170:171], v[178:179], 0, s[30:31]
	s_mov_b32 m0, s20
	s_nop 0
	global_load_lds_dwordx4 v[170:171], off
	v_lshl_add_u64 v[170:171], v[180:181], 0, s[30:31]
	s_add_i32 m0, s20, 0x2000
	s_nop 0
	global_load_lds_dwordx4 v[170:171], off
	v_lshl_add_u64 v[170:171], v[244:245], 0, s[30:31]
	s_mov_b32 m0, s42
	s_nop 0
	global_load_lds_dwordx4 v[170:171], off
	v_lshl_add_u64 v[170:171], v[246:247], 0, s[30:31]
	s_mov_b32 m0, s43
	s_nop 0
	global_load_lds_dwordx4 v[170:171], off
	s_waitcnt vmcnt(8)
	s_waitcnt lgkmcnt(0)
	s_barrier
	s_setprio 1
	s_waitcnt lgkmcnt(0)
	v_mfma_f32_16x16x32_bf16 v[60:63], v[144:147], v[212:215], v[60:63]
	v_mfma_f32_16x16x32_bf16 v[56:59], v[152:155], v[212:215], v[56:59]
	v_mfma_f32_16x16x32_bf16 v[44:47], v[144:147], v[220:223], v[44:47]
	v_mfma_f32_16x16x32_bf16 v[40:43], v[152:155], v[220:223], v[40:43]
	v_mfma_f32_16x16x32_bf16 v[28:31], v[144:147], v[228:231], v[28:31]
	v_mfma_f32_16x16x32_bf16 v[24:27], v[152:155], v[228:231], v[24:27]
	v_mfma_f32_16x16x32_bf16 v[12:15], v[144:147], v[236:239], v[12:15]
	v_mfma_f32_16x16x32_bf16 v[8:11], v[152:155], v[236:239], v[8:11]
	v_mfma_f32_16x16x32_bf16 v[60:63], v[148:151], v[216:219], v[60:63]
	v_mfma_f32_16x16x32_bf16 v[56:59], v[192:195], v[216:219], v[56:59]
	v_mfma_f32_16x16x32_bf16 v[44:47], v[148:151], v[224:227], v[44:47]
	v_mfma_f32_16x16x32_bf16 v[40:43], v[192:195], v[224:227], v[40:43]
	v_mfma_f32_16x16x32_bf16 v[28:31], v[148:151], v[232:235], v[28:31]
	v_mfma_f32_16x16x32_bf16 v[24:27], v[192:195], v[232:235], v[24:27]
	v_mfma_f32_16x16x32_bf16 v[12:15], v[148:151], v[240:243], v[12:15]
	v_mfma_f32_16x16x32_bf16 v[8:11], v[192:195], v[240:243], v[8:11]
	s_setprio 0
	s_setprio 1
	v_mfma_f32_16x16x32_bf16 v[52:55], v[196:199], v[212:215], v[52:55]
	v_mfma_f32_16x16x32_bf16 v[48:51], v[204:207], v[212:215], v[48:51]
	v_mfma_f32_16x16x32_bf16 v[36:39], v[196:199], v[220:223], v[36:39]
	v_mfma_f32_16x16x32_bf16 v[32:35], v[204:207], v[220:223], v[32:35]
	v_mfma_f32_16x16x32_bf16 v[20:23], v[196:199], v[228:231], v[20:23]
	v_mfma_f32_16x16x32_bf16 v[16:19], v[204:207], v[228:231], v[16:19]
	v_mfma_f32_16x16x32_bf16 v[4:7], v[196:199], v[236:239], v[4:7]
	v_mfma_f32_16x16x32_bf16 v[0:3], v[204:207], v[236:239], v[0:3]
	v_mfma_f32_16x16x32_bf16 v[52:55], v[200:203], v[216:219], v[52:55]
	v_mfma_f32_16x16x32_bf16 v[48:51], v[208:211], v[216:219], v[48:51]
	v_mfma_f32_16x16x32_bf16 v[36:39], v[200:203], v[224:227], v[36:39]
	v_mfma_f32_16x16x32_bf16 v[32:35], v[208:211], v[224:227], v[32:35]
	v_mfma_f32_16x16x32_bf16 v[20:23], v[200:203], v[232:235], v[20:23]
	v_mfma_f32_16x16x32_bf16 v[16:19], v[208:211], v[232:235], v[16:19]
	v_mfma_f32_16x16x32_bf16 v[4:7], v[200:203], v[240:243], v[4:7]
	v_mfma_f32_16x16x32_bf16 v[0:3], v[208:211], v[240:243], v[0:3]
	s_setprio 0
	s_barrier
	s_add_u32 s18, s18, 0x100
	s_addc_u32 s19, s19, 0
	s_add_u32 s35, s35, 0x100
	s_addc_u32 s53, s53, 0
	s_cmp_ge_u32 s54, s44
	s_mov_b32 s20, s54
	s_cbranch_scc1 .Lzp3_done
	.p2alignl 6, 3212836864

.LBB0_673:
	v_readlane_b32 s38, v255, 16
	v_readlane_b32 s39, v255, 17
	s_andn2_b64 vcc, exec, s[38:39]
	s_cbranch_vccnz .LBB0_713
	s_add_u32 s20, s20, 0x80
	s_addc_u32 s21, s21, 0
	s_add_u32 s38, s22, 0x100
	s_addc_u32 s39, s23, 0
	s_mov_b32 s22, 0
	s_add_i32 s54, s22, 2
	s_add_u32 s55, s20, 0x80
	s_addc_u32 s23, s21, 0
	s_add_i32 s58, s33, 0x100
	s_cmp_eq_u32 s44, s22
	s_cselect_b32 s23, s1, s23
	s_cselect_b32 s22, s0, s55
	v_add_u32_e32 v112, s58, v147
	s_cselect_b32 s57, s19, s39
	s_cselect_b32 s56, s18, s38
	s_add_i32 s55, s29, 0x100
	ds_read_b128 v[150:153], v112
	ds_read_b128 v[190:193], v112 offset:1024
	ds_read_b128 v[194:197], v112 offset:2048
	ds_read_b128 v[198:201], v112 offset:3072
	v_add_u32_e32 v112, s55, v147
	ds_read_b128 v[202:205], v112
	ds_read_b128 v[206:209], v112 offset:1024
	ds_read_b128 v[210:213], v112 offset:2048
	ds_read_b128 v[214:217], v112 offset:3072
	v_lshl_add_u64 v[114:115], s[20:21], 0, v[140:141]
	s_add_i32 m0, s27, 0xc000
	ds_read_b128 v[218:221], v149
	ds_read_b128 v[222:225], v149 offset:1024
	ds_read_b128 v[226:229], v149 offset:2048
	ds_read_b128 v[230:233], v149 offset:3072
	ds_read_b128 v[234:237], v149 offset:4096
	ds_read_b128 v[238:241], v149 offset:5120
	ds_read_b128 v[242:245], v149 offset:6144
	ds_read_b128 v[246:249], v149 offset:7168
	global_load_lds_dwordx4 v[114:115], off
	v_lshl_add_u64 v[114:115], s[20:21], 0, v[142:143]
	s_add_i32 m0, s27, 0xe000
	s_nop 0
	global_load_lds_dwordx4 v[114:115], off
	s_waitcnt vmcnt(8)
	s_waitcnt lgkmcnt(0)
	s_barrier
	s_setprio 1
	s_waitcnt lgkmcnt(0)
	v_mfma_f32_16x16x32_bf16 v[128:131], v[150:153], v[218:221], 0
	v_mfma_f32_16x16x32_bf16 v[124:127], v[194:197], v[218:221], 0
	v_mfma_f32_16x16x32_bf16 v[108:111], v[150:153], v[226:229], 0
	v_mfma_f32_16x16x32_bf16 v[104:107], v[194:197], v[226:229], 0
	v_mfma_f32_16x16x32_bf16 v[92:95], v[150:153], v[234:237], 0
	v_mfma_f32_16x16x32_bf16 v[88:91], v[194:197], v[234:237], 0
	v_mfma_f32_16x16x32_bf16 v[76:79], v[150:153], v[242:245], 0
	v_mfma_f32_16x16x32_bf16 v[72:75], v[194:197], v[242:245], 0
	v_mfma_f32_16x16x32_bf16 v[128:131], v[190:193], v[222:225], v[128:131]
	v_mfma_f32_16x16x32_bf16 v[124:127], v[198:201], v[222:225], v[124:127]
	v_mfma_f32_16x16x32_bf16 v[108:111], v[190:193], v[230:233], v[108:111]
	v_mfma_f32_16x16x32_bf16 v[104:107], v[198:201], v[230:233], v[104:107]
	v_mfma_f32_16x16x32_bf16 v[92:95], v[190:193], v[238:241], v[92:95]
	v_mfma_f32_16x16x32_bf16 v[88:91], v[198:201], v[238:241], v[88:91]
	v_mfma_f32_16x16x32_bf16 v[76:79], v[190:193], v[246:249], v[76:79]
	v_mfma_f32_16x16x32_bf16 v[72:75], v[198:201], v[246:249], v[72:75]
	s_setprio 0
	s_setprio 1
	v_mfma_f32_16x16x32_bf16 v[120:123], v[202:205], v[218:221], 0
	v_mfma_f32_16x16x32_bf16 v[114:117], v[210:213], v[218:221], 0
	v_mfma_f32_16x16x32_bf16 v[100:103], v[202:205], v[226:229], 0
	v_mfma_f32_16x16x32_bf16 v[96:99], v[210:213], v[226:229], 0
	v_mfma_f32_16x16x32_bf16 v[84:87], v[202:205], v[234:237], 0
	v_mfma_f32_16x16x32_bf16 v[80:83], v[210:213], v[234:237], 0
	v_mfma_f32_16x16x32_bf16 v[68:71], v[202:205], v[242:245], 0
	v_mfma_f32_16x16x32_bf16 v[64:67], v[210:213], v[242:245], 0
	v_mfma_f32_16x16x32_bf16 v[120:123], v[206:209], v[222:225], v[120:123]
	v_mfma_f32_16x16x32_bf16 v[114:117], v[214:217], v[222:225], v[114:117]
	v_mfma_f32_16x16x32_bf16 v[100:103], v[206:209], v[230:233], v[100:103]
	v_mfma_f32_16x16x32_bf16 v[96:99], v[214:217], v[230:233], v[96:99]
	v_mfma_f32_16x16x32_bf16 v[84:87], v[206:209], v[238:241], v[84:87]
	v_mfma_f32_16x16x32_bf16 v[80:83], v[214:217], v[238:241], v[80:83]
	v_mfma_f32_16x16x32_bf16 v[68:71], v[206:209], v[246:249], v[68:71]
	v_mfma_f32_16x16x32_bf16 v[64:67], v[214:217], v[246:249], v[64:67]
	s_setprio 0
	s_barrier
	s_add_i32 s58, s58, s26
	v_lshl_add_u64 v[144:145], s[56:57], 0, v[134:135]
	s_mov_b32 m0, s58
	ds_read_b128 v[218:221], v149 offset:16384
	ds_read_b128 v[222:225], v149 offset:17408
	ds_read_b128 v[226:229], v149 offset:18432
	ds_read_b128 v[230:233], v149 offset:19456
	ds_read_b128 v[234:237], v149 offset:20480
	ds_read_b128 v[238:241], v149 offset:21504
	ds_read_b128 v[242:245], v149 offset:22528
	ds_read_b128 v[246:249], v149 offset:23552
	global_load_lds_dwordx4 v[144:145], off
	s_add_i32 m0, s58, 0x2000
	v_lshl_add_u64 v[154:155], s[56:57], 0, v[138:139]
	s_add_u32 s56, s56, s100
	s_addc_u32 s57, s57, 0
	s_add_i32 s55, s55, s26
	global_load_lds_dwordx4 v[154:155], off
	v_lshl_add_u64 v[170:171], s[56:57], 0, v[134:135]
	s_mov_b32 m0, s55
	v_lshl_add_u64 v[176:177], s[56:57], 0, v[138:139]
	global_load_lds_dwordx4 v[170:171], off
	s_add_i32 m0, s55, 0x2000
	v_lshl_add_u64 v[178:179], s[22:23], 0, v[132:133]
	global_load_lds_dwordx4 v[176:177], off
	s_mov_b32 m0, s27
	v_lshl_add_u64 v[180:181], s[22:23], 0, v[136:137]
	global_load_lds_dwordx4 v[178:179], off
	s_mov_b32 m0, s35
	s_nop 0
	global_load_lds_dwordx4 v[180:181], off
	s_waitcnt vmcnt(8)
	s_waitcnt lgkmcnt(0)
	s_barrier
	s_setprio 1
	s_waitcnt lgkmcnt(0)
	v_mfma_f32_16x16x32_bf16 v[60:63], v[150:153], v[218:221], 0
	v_mfma_f32_16x16x32_bf16 v[56:59], v[194:197], v[218:221], 0
	v_mfma_f32_16x16x32_bf16 v[44:47], v[150:153], v[226:229], 0
	v_mfma_f32_16x16x32_bf16 v[40:43], v[194:197], v[226:229], 0
	v_mfma_f32_16x16x32_bf16 v[28:31], v[150:153], v[234:237], 0
	v_mfma_f32_16x16x32_bf16 v[24:27], v[194:197], v[234:237], 0
	v_mfma_f32_16x16x32_bf16 v[12:15], v[150:153], v[242:245], 0
	v_mfma_f32_16x16x32_bf16 v[8:11], v[194:197], v[242:245], 0
	v_mfma_f32_16x16x32_bf16 v[60:63], v[190:193], v[222:225], v[60:63]
	v_mfma_f32_16x16x32_bf16 v[56:59], v[198:201], v[222:225], v[56:59]
	v_mfma_f32_16x16x32_bf16 v[44:47], v[190:193], v[230:233], v[44:47]
	v_mfma_f32_16x16x32_bf16 v[40:43], v[198:201], v[230:233], v[40:43]
	v_mfma_f32_16x16x32_bf16 v[28:31], v[190:193], v[238:241], v[28:31]
	v_mfma_f32_16x16x32_bf16 v[24:27], v[198:201], v[238:241], v[24:27]
	v_mfma_f32_16x16x32_bf16 v[12:15], v[190:193], v[246:249], v[12:15]
	v_mfma_f32_16x16x32_bf16 v[8:11], v[198:201], v[246:249], v[8:11]
	s_setprio 0
	s_setprio 1
	v_mfma_f32_16x16x32_bf16 v[52:55], v[202:205], v[218:221], 0
	v_mfma_f32_16x16x32_bf16 v[48:51], v[210:213], v[218:221], 0
	v_mfma_f32_16x16x32_bf16 v[36:39], v[202:205], v[226:229], 0
	v_mfma_f32_16x16x32_bf16 v[32:35], v[210:213], v[226:229], 0
	v_mfma_f32_16x16x32_bf16 v[20:23], v[202:205], v[234:237], 0
	v_mfma_f32_16x16x32_bf16 v[16:19], v[210:213], v[234:237], 0
	v_mfma_f32_16x16x32_bf16 v[4:7], v[202:205], v[242:245], 0
	v_mfma_f32_16x16x32_bf16 v[0:3], v[210:213], v[242:245], 0
	v_mfma_f32_16x16x32_bf16 v[52:55], v[206:209], v[222:225], v[52:55]
	v_mfma_f32_16x16x32_bf16 v[48:51], v[214:217], v[222:225], v[48:51]
	v_mfma_f32_16x16x32_bf16 v[36:39], v[206:209], v[230:233], v[36:39]
	v_mfma_f32_16x16x32_bf16 v[32:35], v[214:217], v[230:233], v[32:35]
	v_mfma_f32_16x16x32_bf16 v[20:23], v[206:209], v[238:241], v[20:23]
	v_mfma_f32_16x16x32_bf16 v[16:19], v[214:217], v[238:241], v[16:19]
	v_mfma_f32_16x16x32_bf16 v[4:7], v[206:209], v[246:249], v[4:7]
	v_mfma_f32_16x16x32_bf16 v[0:3], v[214:217], v[246:249], v[0:3]
	s_setprio 0
	s_barrier
	s_add_i32 s55, s8, 0x100
	v_add_u32_e32 v112, s55, v147
	s_add_i32 s56, s9, 0x100
	ds_read_b128 v[150:153], v112
	ds_read_b128 v[190:193], v112 offset:1024
	ds_read_b128 v[194:197], v112 offset:2048
	ds_read_b128 v[198:201], v112 offset:3072
	v_add_u32_e32 v112, s56, v147
	ds_read_b128 v[202:205], v112
	ds_read_b128 v[206:209], v112 offset:1024
	ds_read_b128 v[210:213], v112 offset:2048
	ds_read_b128 v[214:217], v112 offset:3072
	s_add_u32 s22, s22, s10
	s_addc_u32 s23, s23, 0
	s_mov_b32 m0, s40
	v_lshl_add_u64 v[118:119], s[22:23], 0, v[132:133]
	ds_read_b128 v[218:221], v149 offset:32768
	ds_read_b128 v[222:225], v149 offset:33792
	ds_read_b128 v[226:229], v149 offset:34816
	ds_read_b128 v[230:233], v149 offset:35840
	ds_read_b128 v[234:237], v149 offset:36864
	ds_read_b128 v[238:241], v149 offset:37888
	ds_read_b128 v[242:245], v149 offset:38912
	ds_read_b128 v[246:249], v149 offset:39936
	global_load_lds_dwordx4 v[118:119], off
	v_lshl_add_u64 v[118:119], s[22:23], 0, v[136:137]
	s_mov_b32 m0, s41
	s_nop 0
	global_load_lds_dwordx4 v[118:119], off
	s_waitcnt vmcnt(8)
	s_waitcnt lgkmcnt(0)
	s_barrier
	s_setprio 1
	s_waitcnt lgkmcnt(0)
	v_mfma_f32_16x16x32_bf16 v[128:131], v[150:153], v[218:221], v[128:131]
	v_mfma_f32_16x16x32_bf16 v[124:127], v[194:197], v[218:221], v[124:127]
	v_mfma_f32_16x16x32_bf16 v[108:111], v[150:153], v[226:229], v[108:111]
	v_mfma_f32_16x16x32_bf16 v[104:107], v[194:197], v[226:229], v[104:107]
	v_mfma_f32_16x16x32_bf16 v[92:95], v[150:153], v[234:237], v[92:95]
	v_mfma_f32_16x16x32_bf16 v[88:91], v[194:197], v[234:237], v[88:91]
	v_mfma_f32_16x16x32_bf16 v[76:79], v[150:153], v[242:245], v[76:79]
	v_mfma_f32_16x16x32_bf16 v[72:75], v[194:197], v[242:245], v[72:75]
	v_mfma_f32_16x16x32_bf16 v[128:131], v[190:193], v[222:225], v[128:131]
	v_mfma_f32_16x16x32_bf16 v[124:127], v[198:201], v[222:225], v[124:127]
	v_mfma_f32_16x16x32_bf16 v[108:111], v[190:193], v[230:233], v[108:111]
	v_mfma_f32_16x16x32_bf16 v[104:107], v[198:201], v[230:233], v[104:107]
	v_mfma_f32_16x16x32_bf16 v[92:95], v[190:193], v[238:241], v[92:95]
	v_mfma_f32_16x16x32_bf16 v[88:91], v[198:201], v[238:241], v[88:91]
	v_mfma_f32_16x16x32_bf16 v[76:79], v[190:193], v[246:249], v[76:79]
	v_mfma_f32_16x16x32_bf16 v[72:75], v[198:201], v[246:249], v[72:75]
	s_setprio 0
	s_setprio 1
	v_mfma_f32_16x16x32_bf16 v[118:121], v[202:205], v[218:221], v[120:123]
	v_mfma_f32_16x16x32_bf16 v[114:117], v[210:213], v[218:221], v[114:117]
	v_mfma_f32_16x16x32_bf16 v[100:103], v[202:205], v[226:229], v[100:103]
	v_mfma_f32_16x16x32_bf16 v[96:99], v[210:213], v[226:229], v[96:99]
	v_mfma_f32_16x16x32_bf16 v[84:87], v[202:205], v[234:237], v[84:87]
	v_mfma_f32_16x16x32_bf16 v[80:83], v[210:213], v[234:237], v[80:83]
	v_mfma_f32_16x16x32_bf16 v[68:71], v[202:205], v[242:245], v[68:71]
	v_mfma_f32_16x16x32_bf16 v[64:67], v[210:213], v[242:245], v[64:67]
	v_mfma_f32_16x16x32_bf16 v[120:123], v[206:209], v[222:225], v[118:121]
	v_mfma_f32_16x16x32_bf16 v[116:119], v[214:217], v[222:225], v[114:117]
	v_mfma_f32_16x16x32_bf16 v[100:103], v[206:209], v[230:233], v[100:103]
	v_mfma_f32_16x16x32_bf16 v[96:99], v[214:217], v[230:233], v[96:99]
	v_mfma_f32_16x16x32_bf16 v[84:87], v[206:209], v[238:241], v[84:87]
	v_mfma_f32_16x16x32_bf16 v[80:83], v[214:217], v[238:241], v[80:83]
	v_mfma_f32_16x16x32_bf16 v[68:71], v[206:209], v[246:249], v[68:71]
	v_mfma_f32_16x16x32_bf16 v[64:67], v[214:217], v[246:249], v[64:67]
	s_setprio 0
	s_barrier
	s_add_i32 s22, s55, s26
	v_lshl_add_u64 v[114:115], v[144:145], 0, s[30:31]
	s_mov_b32 m0, s22
	ds_read_b128 v[218:221], v149 offset:49152
	ds_read_b128 v[222:225], v149 offset:50176
	ds_read_b128 v[226:229], v149 offset:51200
	ds_read_b128 v[230:233], v149 offset:52224
	ds_read_b128 v[234:237], v149 offset:53248
	ds_read_b128 v[238:241], v149 offset:54272
	ds_read_b128 v[242:245], v149 offset:55296
	ds_read_b128 v[246:249], v149 offset:56320
	global_load_lds_dwordx4 v[114:115], off
	v_lshl_add_u64 v[114:115], v[154:155], 0, s[30:31]
	s_add_i32 m0, s22, 0x2000
	s_add_i32 s22, s56, s26
	global_load_lds_dwordx4 v[114:115], off
	v_lshl_add_u64 v[114:115], v[170:171], 0, s[30:31]
	s_mov_b32 m0, s22
	s_nop 0
	global_load_lds_dwordx4 v[114:115], off
	v_lshl_add_u64 v[114:115], v[176:177], 0, s[30:31]
	s_add_i32 m0, s22, 0x2000
	s_nop 0
	global_load_lds_dwordx4 v[114:115], off
	v_lshl_add_u64 v[114:115], v[178:179], 0, s[30:31]
	s_mov_b32 m0, s42
	s_nop 0
	global_load_lds_dwordx4 v[114:115], off
	v_lshl_add_u64 v[114:115], v[180:181], 0, s[30:31]
	s_mov_b32 m0, s43
	s_nop 0
	global_load_lds_dwordx4 v[114:115], off
	s_waitcnt vmcnt(8)
	s_waitcnt lgkmcnt(0)
	s_barrier
	s_setprio 1
	s_waitcnt lgkmcnt(0)
	v_mfma_f32_16x16x32_bf16 v[60:63], v[150:153], v[218:221], v[60:63]
	v_mfma_f32_16x16x32_bf16 v[56:59], v[194:197], v[218:221], v[56:59]
	v_mfma_f32_16x16x32_bf16 v[44:47], v[150:153], v[226:229], v[44:47]
	v_mfma_f32_16x16x32_bf16 v[40:43], v[194:197], v[226:229], v[40:43]
	v_mfma_f32_16x16x32_bf16 v[28:31], v[150:153], v[234:237], v[28:31]
	v_mfma_f32_16x16x32_bf16 v[24:27], v[194:197], v[234:237], v[24:27]
	v_mfma_f32_16x16x32_bf16 v[12:15], v[150:153], v[242:245], v[12:15]
	v_mfma_f32_16x16x32_bf16 v[8:11], v[194:197], v[242:245], v[8:11]
	v_mfma_f32_16x16x32_bf16 v[60:63], v[190:193], v[222:225], v[60:63]
	v_mfma_f32_16x16x32_bf16 v[56:59], v[198:201], v[222:225], v[56:59]
	v_mfma_f32_16x16x32_bf16 v[44:47], v[190:193], v[230:233], v[44:47]
	v_mfma_f32_16x16x32_bf16 v[40:43], v[198:201], v[230:233], v[40:43]
	v_mfma_f32_16x16x32_bf16 v[28:31], v[190:193], v[238:241], v[28:31]
	v_mfma_f32_16x16x32_bf16 v[24:27], v[198:201], v[238:241], v[24:27]
	v_mfma_f32_16x16x32_bf16 v[12:15], v[190:193], v[246:249], v[12:15]
	v_mfma_f32_16x16x32_bf16 v[8:11], v[198:201], v[246:249], v[8:11]
	s_setprio 0
	s_setprio 1
	v_mfma_f32_16x16x32_bf16 v[52:55], v[202:205], v[218:221], v[52:55]
	v_mfma_f32_16x16x32_bf16 v[48:51], v[210:213], v[218:221], v[48:51]
	v_mfma_f32_16x16x32_bf16 v[36:39], v[202:205], v[226:229], v[36:39]
	v_mfma_f32_16x16x32_bf16 v[32:35], v[210:213], v[226:229], v[32:35]
	v_mfma_f32_16x16x32_bf16 v[20:23], v[202:205], v[234:237], v[20:23]
	v_mfma_f32_16x16x32_bf16 v[16:19], v[210:213], v[234:237], v[16:19]
	v_mfma_f32_16x16x32_bf16 v[4:7], v[202:205], v[242:245], v[4:7]
	v_mfma_f32_16x16x32_bf16 v[0:3], v[210:213], v[242:245], v[0:3]
	v_mfma_f32_16x16x32_bf16 v[52:55], v[206:209], v[222:225], v[52:55]
	v_mfma_f32_16x16x32_bf16 v[48:51], v[214:217], v[222:225], v[48:51]
	v_mfma_f32_16x16x32_bf16 v[36:39], v[206:209], v[230:233], v[36:39]
	v_mfma_f32_16x16x32_bf16 v[32:35], v[214:217], v[230:233], v[32:35]
	v_mfma_f32_16x16x32_bf16 v[20:23], v[206:209], v[238:241], v[20:23]
	v_mfma_f32_16x16x32_bf16 v[16:19], v[214:217], v[238:241], v[16:19]
	v_mfma_f32_16x16x32_bf16 v[4:7], v[206:209], v[246:249], v[4:7]
	v_mfma_f32_16x16x32_bf16 v[0:3], v[214:217], v[246:249], v[0:3]
	s_setprio 0
	s_barrier
	s_add_u32 s20, s20, 0x100
	s_addc_u32 s21, s21, 0
	s_add_u32 s38, s38, 0x100
	s_addc_u32 s39, s39, 0
	s_cmp_ge_u32 s54, s34
	s_mov_b32 s22, s54
	s_cbranch_scc1 .Lzp1_done
	.p2alignl 6, 3212836864
